# grid barrier: L1 invalidate issued at arrive time instead of after the poll (off the critical path)
# speedup vs baseline: 1.0799x; 1.0799x over previous
; __device__ __forceinline__ unsigned xb_add(unsigned* p, unsigned v) { return __hip_atomic_fetch_add(p, v, __ATOMIC_RELAXED, __HIP_MEMORY_SCOPE_AGENT); }
; __device__ __forceinline__ void xcd_barrier(const XcdBarrier& b) {
;     asm volatile("s_waitcnt vmcnt(0)" ::: "memory");
;     __syncthreads();
;     if (threadIdx.x == 0) {
;         unsigned* bar = b.bar;
;         __builtin_amdgcn_s_waitcnt(0);
;         unsigned nloc = b.st[0], nx = b.st[1];
;         if (nloc == 0u) { xcd_barrier_complete(bar, b.x, nloc, nx); b.st[0] = nloc; b.st[1] = nx; }
;         const unsigned old = xb_add(&bar[XB_XSUB(b.x)], 1u);
.LBB0_70:
	s_mov_b64 s[8:9], exec
	v_mbcnt_lo_u32_b32 v2, s8, 0
	v_mbcnt_hi_u32_b32 v2, s9, v2
	v_cmp_eq_u32_e32 vcc, 0, v2
	s_and_saveexec_b64 s[6:7], vcc
	s_cbranch_execz .LBB0_72
	s_lshl_b32 s10, s33, 8
	s_add_u32 s10, s82, s10
	s_addc_u32 s11, s83, 0
	s_bcnt1_i32_b64 s8, s[8:9]
	v_mov_b32_e32 v4, 0x1000
	v_mov_b32_e32 v5, s8
	buffer_inv sc1
	global_atomic_add v4, v4, v5, s[10:11] offset:1024 sc0

; __device__ __forceinline__ unsigned xb_ld(unsigned* p)              { return __hip_atomic_load(p, __ATOMIC_RELAXED, __HIP_MEMORY_SCOPE_AGENT); }
; __device__ __forceinline__ unsigned xb_add(unsigned* p, unsigned v) { return __hip_atomic_fetch_add(p, v, __ATOMIC_RELAXED, __HIP_MEMORY_SCOPE_AGENT); }
; #define XB_SPIN(cond, bar) do { unsigned _sp = 0; while (cond) { __builtin_amdgcn_s_sleep(1); \
;     if ((++_sp & 255u) == 0u) { if (xb_ld(&(bar)[XB_TMO])) break; if (_sp > XB_SPIN_CAP) { atomicAdd(&(bar)[XB_TMO], 1u); break; } } } } while (0)
; __device__ __forceinline__ void xcd_barrier(const XcdBarrier& b) {
;     ...
;             const unsigned og = xb_add(&bar[XB_TOP], 1u);
;             const unsigned tg = og / nx;
;             if (og + 1u == (tg + 1u) * nx) xb_add(&bar[XB_TOPGEN], 1u);
;             else XB_SPIN(xb_ld(&bar[XB_TOPGEN]) == tg, bar);
;             __builtin_amdgcn_fence(__ATOMIC_ACQUIRE, "agent");
;             asm volatile("s_waitcnt vmcnt(0)" ::: "memory");
;         } else {
;             XB_SPIN(xb_ld(&bar[XB_TOPGEN]) == gen, bar);
;             __builtin_amdgcn_fence(__ATOMIC_ACQUIRE, "agent");
;             asm volatile("s_waitcnt vmcnt(0)" ::: "memory");
.LBB0_85:
	s_or_b64 exec, exec, s[8:9]
	s_waitcnt vmcnt(0)
.LBB0_86:
	s_andn2_saveexec_b64 s[6:7], s[6:7]
	s_cbranch_execz .LBB0_104
	s_mov_b64 s[6:7], exec
	buffer_wbl2 sc1
	s_waitcnt lgkmcnt(0)
	s_waitcnt vmcnt(0)
	v_mbcnt_lo_u32_b32 v2, s6, 0
	v_mbcnt_hi_u32_b32 v2, s7, v2
	v_cmp_eq_u32_e32 vcc, 0, v2
	s_and_saveexec_b64 s[8:9], vcc
	s_cbranch_execz .LBB0_89
	s_bcnt1_i32_b64 s6, s[6:7]
	v_mov_b32_e32 v3, 0x7000
	v_mov_b32_e32 v4, s6
	global_atomic_add v3, v3, v4, s[30:31] offset:1024 sc0

; __device__ __forceinline__ unsigned xb_ld(unsigned* p)              { return __hip_atomic_load(p, __ATOMIC_RELAXED, __HIP_MEMORY_SCOPE_AGENT); }
; #define XB_SPIN(cond, bar) do { unsigned _sp = 0; while (cond) { __builtin_amdgcn_s_sleep(1); \
;     if ((++_sp & 255u) == 0u) { if (xb_ld(&(bar)[XB_TMO])) break; if (_sp > XB_SPIN_CAP) { atomicAdd(&(bar)[XB_TMO], 1u); break; } } } } while (0)
; __device__ __forceinline__ void xcd_barrier(const XcdBarrier& b) {
;     ...
;         } else {
;             XB_SPIN(xb_ld(&bar[XB_TOPGEN]) == gen, bar);
;             __builtin_amdgcn_fence(__ATOMIC_ACQUIRE, "agent");
;             asm volatile("s_waitcnt vmcnt(0)" ::: "memory");
;         }
;     }
;     __syncthreads();
; }
;     __device__ __forceinline__ bool next(int i, Unit& u) const {
;         int L = i * G + c; if (L >= G1_ALL) return false;
;         u.nt = DM / 64; u.kind = 0;
;         if (L < G1_SPECIAL) { u.pm = MP / 256 + (L >> 3); u.pn = 30 + (L & 7); u.kind = 4; }
;         else if ((L -= G1_SPECIAL) < G1_PROMPT) { int pm, pn; pg8::tile_order(L, MP / 256, G1_NN, pm, pn); u.pm = pm; u.pn = pn; }
;         else if ((L -= G1_PROMPT) < G1_S2) { u.pm = MP / 256 + L / 30; u.pn = L % 30; }
;         else { const int r = L - G1_S2, t = r >> 4, pm = (r >> 2) & 3, pn = r & 3; u.pm = pm; u.pn = pn; u.kind = 1 + t;
;             if (t == 0) { u.A = HM + (size_t)pm * TSTEP4K; u.B = WKV + (size_t)pn * TSTEP4K; }
;             else if (t == 1) { u.A = HM + (size_t)pm * TSTEP4K; u.B = WKV + (size_t)(4 + pn) * TSTEP4K; }
;             else { u.A = WKV + (size_t)(4 + pm) * TSTEP4K; u.B = HM + (size_t)pn * TSTEP4K; }
;             return true; }
;         u.A = H + (size_t)u.pm * TSTEP4K; u.B = WIN + (size_t)u.pn * TSTEP4K;
;         return true;
.LBB0_103:
	s_or_b64 exec, exec, s[6:7]
	s_waitcnt vmcnt(0)
.LBB0_104:
	s_or_b64 exec, exec, s[4:5]
	s_waitcnt lgkmcnt(0)
	v_mov_b32_e32 v1, v0
	s_mov_b64 s[4:5], s[0:1]
	s_barrier
	s_load_dwordx4 s[8:11], s[4:5], 0xa8
	s_load_dwordx4 s[24:27], s[0:1], 0x70
	v_mov_b32_e32 v10, v0
	s_waitcnt lgkmcnt(0)
	s_add_u32 s29, s10, 0x1ba00000
	s_addc_u32 s74, s11, 0
	s_add_u32 s75, s10, 0x1b200000
	s_addc_u32 s76, s11, 0
	s_add_u32 s77, s10, 0x20e00000
	s_addc_u32 s78, s11, 0
	s_add_u32 s79, s10, 0x1fe00000
	s_addc_u32 s80, s11, 0
	s_cmpk_lt_i32 s2, 0x53c
	s_cselect_b64 s[6:7], -1, 0
	s_cmpk_gt_i32 s2, 0x53b
	v_readfirstlane_b32 s12, v10
	s_cbranch_scc1 .LBB0_111
	s_cmp_gt_i32 s2, 15
	s_cbranch_scc0 .LBB0_112
	s_cmpk_gt_u32 s2, 0x4cf
	s_cbranch_scc0 .LBB0_113
	s_cmpk_gt_u32 s2, 0x50b
	s_cbranch_scc0 .LBB0_114
	s_add_i32 s13, s2, 0xfffffaf4
	s_lshr_b32 s16, s13, 4
	s_bfe_u32 s4, s13, 0x20002
	s_and_b32 s62, s2, 3
	s_add_i32 s5, s16, 1
	s_cmp_gt_u32 s13, 15
	s_cbranch_scc0 .LBB0_115
	s_lshl_b32 s18, s4, 21
	s_cmp_lg_u32 s16, 1
	s_cbranch_scc0 .LBB0_116
	s_add_u32 s16, s79, s18
	s_addc_u32 s17, s80, 0
	s_add_u32 s66, s16, 0x800000
	s_addc_u32 s67, s17, 0
	s_lshl_b32 s16, s62, 21
	s_add_u32 s68, s75, s16
	s_addc_u32 s69, s76, 0
	s_mov_b64 s[16:17], 0
	s_branch .LBB0_117

; __device__ __forceinline__ unsigned xb_ld(unsigned* p)              { return __hip_atomic_load(p, __ATOMIC_RELAXED, __HIP_MEMORY_SCOPE_AGENT); }
; #define XB_SPIN(cond, bar) do { unsigned _sp = 0; while (cond) { __builtin_amdgcn_s_sleep(1); \
;     if ((++_sp & 255u) == 0u) { if (xb_ld(&(bar)[XB_TMO])) break; if (_sp > XB_SPIN_CAP) { atomicAdd(&(bar)[XB_TMO], 1u); break; } } } } while (0)
; __device__ __forceinline__ void xcd_barrier_wait(const XcdBarrier& b, const XbState& st) {
;     unsigned* bar = b.bar;
;     if (threadIdx.x == 0) {
;         if (st.lastx) {
;             if (!st.lastt) XB_SPIN(xb_ld(&bar[XB_TOPGEN]) == st.tg, bar);
;             __builtin_amdgcn_fence(__ATOMIC_ACQUIRE, "agent");
;             asm volatile("s_waitcnt vmcnt(0)" ::: "memory");
;         } else {
;             XB_SPIN(xb_ld(&bar[XB_TOPGEN]) == st.gen, bar);
;             __builtin_amdgcn_fence(__ATOMIC_ACQUIRE, "agent");
;             asm volatile("s_waitcnt vmcnt(0)" ::: "memory");
.LBB0_396:
	s_or_b64 exec, exec, s[10:11]
	s_waitcnt vmcnt(0)
.LBB0_397:
	s_andn2_saveexec_b64 s[8:9], s[8:9]
	s_cbranch_execz .LBB0_412
	s_xor_b64 s[8:9], s[6:7], -1
	s_and_saveexec_b64 s[6:7], s[8:9]
	s_cbranch_execz .LBB0_411
	v_mov_b32_e32 v1, 0x7000
	global_load_dword v1, v1, s[30:31] offset:1280 sc1
	s_add_u32 s10, s30, 0x7500
	s_addc_u32 s11, s31, 0
	s_waitcnt vmcnt(0)
	v_cmp_eq_u32_e32 vcc, v1, v3
	s_and_b64 exec, exec, vcc
	s_cbranch_execz .LBB0_411
	s_add_u32 s8, s30, 0x4200
	s_addc_u32 s9, s31, 0
	s_mov_b32 s12, 1
	s_mov_b64 s[16:17], 0
	v_mov_b32_e32 v2, 0
	s_branch .LBB0_402

; #define LAS __attribute__((address_space(3)))
; __device__ __forceinline__ int fresh_tid() { int t = threadIdx.x; asm volatile("" : "+v"(t)); return t; }
; __device__ __forceinline__ unsigned xb_ld(unsigned* p)              { return __hip_atomic_load(p, __ATOMIC_RELAXED, __HIP_MEMORY_SCOPE_AGENT); }
; #define XB_SPIN(cond, bar) do { unsigned _sp = 0; while (cond) { __builtin_amdgcn_s_sleep(1); \
;     if ((++_sp & 255u) == 0u) { if (xb_ld(&(bar)[XB_TMO])) break; if (_sp > XB_SPIN_CAP) { atomicAdd(&(bar)[XB_TMO], 1u); break; } } } } while (0)
; __device__ __forceinline__ void xcd_barrier_wait(const XcdBarrier& b, const XbState& st) {
;     ...
;     if (threadIdx.x == 0) {
;         if (st.lastx) {
;             if (!st.lastt) XB_SPIN(xb_ld(&bar[XB_TOPGEN]) == st.tg, bar);
;             __builtin_amdgcn_fence(__ATOMIC_ACQUIRE, "agent");
;             asm volatile("s_waitcnt vmcnt(0)" ::: "memory");
;         } else {
;             XB_SPIN(xb_ld(&bar[XB_TOPGEN]) == st.gen, bar);
;             __builtin_amdgcn_fence(__ATOMIC_ACQUIRE, "agent");
;             asm volatile("s_waitcnt vmcnt(0)" ::: "memory");
;         }
;     }
;     __syncthreads();
; }
; __device__ __forceinline__ Frame make_frame(LAS unsigned char* lds) {
;     Frame F; F.lds = lds;
;     F.tid = fresh_tid(); F.lane = F.tid & 63; F.wave = __builtin_amdgcn_readfirstlane(F.tid >> 6);
;     F.G = gridDim.x; { const int bx = blockIdx.x; F.vcu = (F.G % 8 == 0) ? (bx % 8) * (F.G / 8) + bx / 8 : bx; }
.LBB0_411:
	s_or_b64 exec, exec, s[6:7]
	s_waitcnt vmcnt(0)
.LBB0_412:
	s_or_b64 exec, exec, s[4:5]
	s_cmpk_lg_i32 s3, 0x100
	v_cndmask_b32_e64 v1, 0, 1, s[70:71]
	s_cselect_b64 s[20:21], -1, 0
	s_cmpk_eq_i32 s3, 0x100
	v_cmp_ne_u32_e64 s[4:5], 1, v1
	s_waitcnt vmcnt(63) expcnt(7) lgkmcnt(15)
	s_barrier
	s_cbranch_scc1 .LBB0_444
	v_mov_b32_e32 v2, v0
	s_and_b64 vcc, exec, s[4:5]
	v_readfirstlane_b32 s8, v2
	s_mov_b32 s29, s2
	s_cbranch_vccnz .LBB0_415
	s_ashr_i32 s7, s2, 31
	s_lshr_b32 s7, s7, 29
	s_add_i32 s7, s2, s7
	s_and_b32 s9, s7, -8
	s_ashr_i32 s6, s3, 3
	s_sub_i32 s9, s2, s9
	s_mul_i32 s6, s6, s9
	s_ashr_i32 s7, s7, 3
	s_add_i32 s29, s6, s7

; __device__ __forceinline__ unsigned xb_add(unsigned* p, unsigned v) { return __hip_atomic_fetch_add(p, v, __ATOMIC_RELAXED, __HIP_MEMORY_SCOPE_AGENT); }
; __device__ __forceinline__ XbState xcd_barrier_arrive(const XcdBarrier& b) {
;     asm volatile("s_waitcnt vmcnt(0)" ::: "memory");
;     __syncthreads();
;     unsigned* bar = b.bar;
;     XbState st; st.gen = 0u; st.tg = 0u; st.lastx = false; st.lastt = false;
;     if (threadIdx.x == 0) {
;         __builtin_amdgcn_s_waitcnt(0);
;         unsigned nloc = b.st[0], nx = b.st[1];
;         if (nloc == 0u) { xcd_barrier_complete(bar, b.x, nloc, nx); b.st[0] = nloc; b.st[1] = nx; }
;         const unsigned old = xb_add(&bar[XB_XSUB(b.x)], 1u);
;         st.gen = old / nloc; st.lastx = (old + 1u == (st.gen + 1u) * nloc);
.LBB0_581:
	s_mov_b64 s[10:11], exec
	v_mbcnt_lo_u32_b32 v1, s10, 0
	v_mbcnt_hi_u32_b32 v2, s11, v1
	v_cmp_eq_u32_e32 vcc, 0, v2
	s_and_saveexec_b64 s[8:9], vcc
	s_cbranch_execz .LBB0_583
	s_lshl_b32 s12, s33, 8
	s_add_u32 s12, s82, s12
	s_addc_u32 s13, s83, 0
	s_bcnt1_i32_b64 s10, s[10:11]
	v_mov_b32_e32 v1, 0x1000
	v_mov_b32_e32 v5, s10
	buffer_inv sc1
	global_atomic_add v5, v1, v5, s[12:13] offset:1024 sc0

; __device__ __forceinline__ unsigned xb_ld(unsigned* p)              { return __hip_atomic_load(p, __ATOMIC_RELAXED, __HIP_MEMORY_SCOPE_AGENT); }
; #define XB_SPIN(cond, bar) do { unsigned _sp = 0; while (cond) { __builtin_amdgcn_s_sleep(1); \
;     if ((++_sp & 255u) == 0u) { if (xb_ld(&(bar)[XB_TMO])) break; if (_sp > XB_SPIN_CAP) { atomicAdd(&(bar)[XB_TMO], 1u); break; } } } } while (0)
; __device__ __forceinline__ void xcd_barrier_wait(const XcdBarrier& b, const XbState& st) {
;     unsigned* bar = b.bar;
;     if (threadIdx.x == 0) {
;         if (st.lastx) {
;             if (!st.lastt) XB_SPIN(xb_ld(&bar[XB_TOPGEN]) == st.tg, bar);
;             __builtin_amdgcn_fence(__ATOMIC_ACQUIRE, "agent");
;             asm volatile("s_waitcnt vmcnt(0)" ::: "memory");
;         } else {
;             XB_SPIN(xb_ld(&bar[XB_TOPGEN]) == st.gen, bar);
;             __builtin_amdgcn_fence(__ATOMIC_ACQUIRE, "agent");
;             asm volatile("s_waitcnt vmcnt(0)" ::: "memory");
.LBB0_612:
	s_or_b64 exec, exec, s[18:19]
	s_waitcnt vmcnt(0) lgkmcnt(0)
.LBB0_613:
	s_andn2_saveexec_b64 s[16:17], s[16:17]
	s_cbranch_execz .LBB0_628
	s_xor_b64 s[16:17], s[8:9], -1
	s_and_saveexec_b64 s[8:9], s[16:17]
	s_cbranch_execz .LBB0_627
	v_mov_b32_e32 v1, 0x7000
	global_load_dword v1, v1, s[30:31] offset:1280 sc1
	s_add_u32 s18, s30, 0x7500
	s_addc_u32 s19, s31, 0
	s_waitcnt vmcnt(0)
	v_cmp_eq_u32_e32 vcc, v1, v3
	s_and_b64 exec, exec, vcc
	s_cbranch_execz .LBB0_627
	s_add_u32 s16, s30, 0x4200
	s_addc_u32 s17, s31, 0
	s_mov_b32 s35, 1
	s_mov_b64 s[20:21], 0
	v_mov_b32_e32 v2, 0
	s_branch .LBB0_618

.LBB0_627:
	s_or_b64 exec, exec, s[8:9]
	s_waitcnt vmcnt(0) lgkmcnt(0)
.LBB0_628:
	s_or_b64 exec, exec, s[12:13]
	v_mov_b32_e32 v6, v0
	s_waitcnt vmcnt(0) lgkmcnt(0)
	s_barrier
	s_andn2_b64 vcc, exec, s[6:7]
	v_readfirstlane_b32 s16, v6
	s_cbranch_vccnz .LBB0_652
	s_ashr_i32 s6, s2, 31
	s_lshr_b32 s6, s6, 29
	s_add_i32 s9, s2, s6
	s_and_b32 s6, s9, -8
	s_sub_i32 s8, s2, s6
	s_cmp_gt_i32 s8, 3
	s_cbranch_scc0 .LBB0_631
	s_mul_i32 s6, s8, 25
	s_add_i32 s12, s6, 4
	s_cbranch_execz .LBB0_632
	s_branch .LBB0_633

; __device__ __forceinline__ unsigned xb_ld(unsigned* p)              { return __hip_atomic_load(p, __ATOMIC_RELAXED, __HIP_MEMORY_SCOPE_AGENT); }
; #define XB_SPIN(cond, bar) do { unsigned _sp = 0; while (cond) { __builtin_amdgcn_s_sleep(1); \
;     if ((++_sp & 255u) == 0u) { if (xb_ld(&(bar)[XB_TMO])) break; if (_sp > XB_SPIN_CAP) { atomicAdd(&(bar)[XB_TMO], 1u); break; } } } } while (0)
; __device__ __forceinline__ void xcd_barrier_wait(const XcdBarrier& b, const XbState& st) {
;     unsigned* bar = b.bar;
;     if (threadIdx.x == 0) {
;         if (st.lastx) {
;             if (!st.lastt) XB_SPIN(xb_ld(&bar[XB_TOPGEN]) == st.tg, bar);
;             __builtin_amdgcn_fence(__ATOMIC_ACQUIRE, "agent");
;             asm volatile("s_waitcnt vmcnt(0)" ::: "memory");
;         } else {
;             XB_SPIN(xb_ld(&bar[XB_TOPGEN]) == st.gen, bar);
;             __builtin_amdgcn_fence(__ATOMIC_ACQUIRE, "agent");
;             asm volatile("s_waitcnt vmcnt(0)" ::: "memory");
.LBB0_723:
	s_or_b64 exec, exec, s[18:19]
	s_waitcnt vmcnt(0) lgkmcnt(0)
.LBB0_724:
	s_andn2_saveexec_b64 s[16:17], s[16:17]
	s_cbranch_execz .LBB0_739
	s_xor_b64 s[16:17], s[8:9], -1
	s_and_saveexec_b64 s[8:9], s[16:17]
	s_cbranch_execz .LBB0_738
	v_mov_b32_e32 v1, 0x7000
	global_load_dword v1, v1, s[30:31] offset:1280 sc1
	s_add_u32 s18, s30, 0x7500
	s_addc_u32 s19, s31, 0
	s_waitcnt vmcnt(0)
	v_cmp_eq_u32_e32 vcc, v1, v3
	s_and_b64 exec, exec, vcc
	s_cbranch_execz .LBB0_738
	s_add_u32 s16, s30, 0x4200
	s_addc_u32 s17, s31, 0
	s_mov_b32 s35, 1
	s_mov_b64 s[20:21], 0
	v_mov_b32_e32 v2, 0
	s_branch .LBB0_729

; __device__ __forceinline__ unsigned xb_ld(unsigned* p)              { return __hip_atomic_load(p, __ATOMIC_RELAXED, __HIP_MEMORY_SCOPE_AGENT); }
; #define XB_SPIN(cond, bar) do { unsigned _sp = 0; while (cond) { __builtin_amdgcn_s_sleep(1); \
;     if ((++_sp & 255u) == 0u) { if (xb_ld(&(bar)[XB_TMO])) break; if (_sp > XB_SPIN_CAP) { atomicAdd(&(bar)[XB_TMO], 1u); break; } } } } while (0)
; __device__ __forceinline__ void xcd_barrier_wait(const XcdBarrier& b, const XbState& st) {
;     ...
;     if (threadIdx.x == 0) {
;         if (st.lastx) {
;             if (!st.lastt) XB_SPIN(xb_ld(&bar[XB_TOPGEN]) == st.tg, bar);
;             __builtin_amdgcn_fence(__ATOMIC_ACQUIRE, "agent");
;             asm volatile("s_waitcnt vmcnt(0)" ::: "memory");
;         } else {
;             XB_SPIN(xb_ld(&bar[XB_TOPGEN]) == st.gen, bar);
;             __builtin_amdgcn_fence(__ATOMIC_ACQUIRE, "agent");
;             asm volatile("s_waitcnt vmcnt(0)" ::: "memory");
;         }
;     }
;     __syncthreads();
; }
;     __device__ __forceinline__ bool next(int i, Unit& u) const {
;         constexpr int NPT = (MP / 256) * 16;
;         const int L = i * G + c;
;         if (L < NPT) { int pm, pn; pg8::tile_order(L, MP / 256, 16, pm, pn); u.pm = pm; u.pn = pn; u.kind = 0; u.nt = DM / 64; u.A = CAT + (size_t)pm * TSTEP4K; u.B = WOUT + (size_t)pn * TSTEP4K; return true; }
;         const int q = L - NPT; if (q >= 256) return false;
;         const int r = q >> 3, p = q & 7, pm = MP / 256 + (r >> 4), pn = r & 15;
;         u.pm = pm; u.pn = pn; u.kind = 1 + p; u.nt = 8; u.A = CAT + (size_t)pm * TSTEP4K + (size_t)p * 1024; u.B = WOUT + (size_t)pn * TSTEP4K + (size_t)p * 1024; return true;
;     }
.LBB0_738:
	s_or_b64 exec, exec, s[8:9]
	s_waitcnt vmcnt(0) lgkmcnt(0)
.LBB0_739:
	s_or_b64 exec, exec, s[12:13]
	s_add_u32 s35, s10, 0xec00000
	v_mov_b32_e32 v6, v0
	s_addc_u32 s36, s11, 0
	s_waitcnt vmcnt(0) lgkmcnt(0)
	s_barrier
	s_and_b64 vcc, exec, s[6:7]
	v_readfirstlane_b32 s16, v6
	s_cbranch_vccz .LBB0_742
	s_cmpk_lt_u32 s2, 0x300
	s_mov_b64 s[6:7], 0
	s_cbranch_scc0 .LBB0_743
	s_add_i32 s8, s2, 0xfffffe00
	s_lshr_b32 s8, s8, 7
	s_and_b32 s12, s2, 7
	s_add_i32 s20, s8, 32
	s_mov_b32 s21, 0
	s_bfe_u32 s62, s2, 0x40003
	s_add_i32 s65, s12, 1
	s_lshl_b64 s[8:9], s[20:21], 21
	s_add_u32 s8, s35, s8
	s_addc_u32 s9, s36, s9
	s_lshl_b32 s12, s12, 10
	s_add_u32 s38, s8, s12
	s_addc_u32 s39, s9, 0
	s_lshl_b32 s8, s62, 21
	s_add_u32 s8, s29, s8
	s_addc_u32 s9, s34, 0
	s_add_u32 s40, s8, s12
	s_addc_u32 s41, s9, 0
	s_mov_b64 s[8:9], -1
	s_mov_b32 s21, 8
	s_and_b64 vcc, exec, s[6:7]
	s_cbranch_vccnz .LBB0_744
	s_branch .LBB0_749

; __device__ __forceinline__ unsigned xb_add(unsigned* p, unsigned v) { return __hip_atomic_fetch_add(p, v, __ATOMIC_RELAXED, __HIP_MEMORY_SCOPE_AGENT); }
; __device__ __forceinline__ XbState xcd_barrier_arrive(const XcdBarrier& b) {
;     asm volatile("s_waitcnt vmcnt(0)" ::: "memory");
;     __syncthreads();
;     unsigned* bar = b.bar;
;     XbState st; st.gen = 0u; st.tg = 0u; st.lastx = false; st.lastt = false;
;     if (threadIdx.x == 0) {
;         __builtin_amdgcn_s_waitcnt(0);
;         unsigned nloc = b.st[0], nx = b.st[1];
;         if (nloc == 0u) { xcd_barrier_complete(bar, b.x, nloc, nx); b.st[0] = nloc; b.st[1] = nx; }
;         const unsigned old = xb_add(&bar[XB_XSUB(b.x)], 1u);
;         st.gen = old / nloc; st.lastx = (old + 1u == (st.gen + 1u) * nloc);
.LBB0_788:
	s_mov_b64 s[10:11], exec
	v_mbcnt_lo_u32_b32 v1, s10, 0
	v_mbcnt_hi_u32_b32 v4, s11, v1
	v_cmp_eq_u32_e32 vcc, 0, v4
	s_and_saveexec_b64 s[8:9], vcc
	s_cbranch_execz .LBB0_790
	s_lshl_b32 s12, s33, 8
	s_add_u32 s12, s82, s12
	s_addc_u32 s13, s83, 0
	s_bcnt1_i32_b64 s10, s[10:11]
	v_mov_b32_e32 v1, 0x1000
	v_mov_b32_e32 v5, s10
	buffer_inv sc1
	global_atomic_add v5, v1, v5, s[12:13] offset:1024 sc0

; __device__ __forceinline__ unsigned xb_ld(unsigned* p)              { return __hip_atomic_load(p, __ATOMIC_RELAXED, __HIP_MEMORY_SCOPE_AGENT); }
; #define XB_SPIN(cond, bar) do { unsigned _sp = 0; while (cond) { __builtin_amdgcn_s_sleep(1); \
;     if ((++_sp & 255u) == 0u) { if (xb_ld(&(bar)[XB_TMO])) break; if (_sp > XB_SPIN_CAP) { atomicAdd(&(bar)[XB_TMO], 1u); break; } } } } while (0)
; __device__ __forceinline__ void xcd_barrier_wait(const XcdBarrier& b, const XbState& st) {
;     unsigned* bar = b.bar;
;     if (threadIdx.x == 0) {
;         if (st.lastx) {
;             if (!st.lastt) XB_SPIN(xb_ld(&bar[XB_TOPGEN]) == st.tg, bar);
;             __builtin_amdgcn_fence(__ATOMIC_ACQUIRE, "agent");
;             asm volatile("s_waitcnt vmcnt(0)" ::: "memory");
;         } else {
;             XB_SPIN(xb_ld(&bar[XB_TOPGEN]) == st.gen, bar);
;             __builtin_amdgcn_fence(__ATOMIC_ACQUIRE, "agent");
;             asm volatile("s_waitcnt vmcnt(0)" ::: "memory");
.LBB0_815:
	s_or_b64 exec, exec, s[12:13]
	s_waitcnt vmcnt(0)
.LBB0_816:
	s_andn2_saveexec_b64 s[10:11], s[10:11]
	s_cbranch_execz .LBB0_831
	s_xor_b64 s[10:11], s[8:9], -1
	s_and_saveexec_b64 s[8:9], s[10:11]
	s_cbranch_execz .LBB0_830
	v_mov_b32_e32 v1, 0x7000
	global_load_dword v1, v1, s[30:31] offset:1280 sc1
	s_add_u32 s12, s30, 0x7500
	s_addc_u32 s13, s31, 0
	s_waitcnt vmcnt(0)
	v_cmp_eq_u32_e32 vcc, v1, v67
	s_and_b64 exec, exec, vcc
	s_cbranch_execz .LBB0_830
	s_add_u32 s10, s30, 0x4200
	s_addc_u32 s11, s31, 0
	s_mov_b32 s24, 1
	s_mov_b64 s[14:15], 0
	v_mov_b32_e32 v1, 0
	s_branch .LBB0_821

; #define LAS __attribute__((address_space(3)))
; __device__ __forceinline__ int fresh_tid() { int t = threadIdx.x; asm volatile("" : "+v"(t)); return t; }
; __device__ __forceinline__ unsigned xb_ld(unsigned* p)              { return __hip_atomic_load(p, __ATOMIC_RELAXED, __HIP_MEMORY_SCOPE_AGENT); }
; #define XB_SPIN(cond, bar) do { unsigned _sp = 0; while (cond) { __builtin_amdgcn_s_sleep(1); \
;     if ((++_sp & 255u) == 0u) { if (xb_ld(&(bar)[XB_TMO])) break; if (_sp > XB_SPIN_CAP) { atomicAdd(&(bar)[XB_TMO], 1u); break; } } } } while (0)
; __device__ __forceinline__ void xcd_barrier_wait(const XcdBarrier& b, const XbState& st) {
;     ...
;             if (!st.lastt) XB_SPIN(xb_ld(&bar[XB_TOPGEN]) == st.tg, bar);
;             __builtin_amdgcn_fence(__ATOMIC_ACQUIRE, "agent");
;             asm volatile("s_waitcnt vmcnt(0)" ::: "memory");
;         } else {
;             XB_SPIN(xb_ld(&bar[XB_TOPGEN]) == st.gen, bar);
;             __builtin_amdgcn_fence(__ATOMIC_ACQUIRE, "agent");
;             asm volatile("s_waitcnt vmcnt(0)" ::: "memory");
;         }
;     }
;     __syncthreads();
; }
; __device__ __forceinline__ Frame make_frame(LAS unsigned char* lds) {
;     Frame F; F.lds = lds;
;     F.tid = fresh_tid(); F.lane = F.tid & 63; F.wave = __builtin_amdgcn_readfirstlane(F.tid >> 6);
;     F.G = gridDim.x; { const int bx = blockIdx.x; F.vcu = (F.G % 8 == 0) ? (bx % 8) * (F.G / 8) + bx / 8 : bx; }
.LBB0_830:
	s_or_b64 exec, exec, s[8:9]
	s_waitcnt vmcnt(0)
.LBB0_831:
	s_or_b64 exec, exec, s[6:7]
	s_barrier
	s_and_b64 vcc, exec, s[4:5]
	v_readfirstlane_b32 s4, v0
	s_cbranch_vccnz .LBB0_833
	s_ashr_i32 s6, s2, 31
	s_lshr_b32 s6, s6, 29
	s_add_i32 s6, s2, s6
	s_ashr_i32 s7, s6, 3
	s_and_b32 s6, s6, -8
	s_ashr_i32 s5, s3, 3
	s_sub_i32 s2, s2, s6
	s_mul_i32 s2, s5, s2
	s_add_i32 s2, s2, s7
